# g1 KdT/QG and rhs-scaling loops hand-unrolled with batched LDS reads
# speedup vs baseline: 1.0083x; 1.0083x over previous
; __device__ __forceinline__ unsigned f2bf(float f) { const f32x2_ v = {f, 0.f}; const bf16x2_ b = __builtin_convertvector(v, bf16x2_); return __builtin_bit_cast(unsigned, b) & 0xffffu; }
; __device__ __forceinline__ void g1_phase(const PP P, int l, LAS unsigned char* lds) {
;     ...
;         if (act) {
;             const float glast = Gs[63];
;             for (int e = gt; e < 4096; e += 256) { const int hi = e >> 6, lo = e & 63;
;                 KdT[e] = (bf16)f2bf(ks[lo * 65 + hi] * __expf(glast - Gs[lo]));
;                 QG[e] = (bf16)f2bf(qs[hi * 65 + lo] * __expf(Gs[hi])); }
;             if (gt == 0) *(float*)(ub + 49152) = __expf(glast);
;         }
.LBB0_594:
	s_or_b64 exec, exec, s[26:27]
	s_waitcnt lgkmcnt(0)
	s_barrier
	s_mov_b32 s26, 0xc100
	v_mad_i64_i32 v[12:13], s[26:27], v69, s26, 0
	s_and_saveexec_b64 s[26:27], s[76:77]
	s_cbranch_execz .LBB0_599
	ds_read_b32 v2, v121
	ds_read_b32 v3, v152
	v_lshl_add_u64 v[0:1], v[66:67], 0, v[12:13]
	s_mov_b64 s[78:79], 0
	v_mov_b32_e32 v4, v110
	v_mov_b32_e32 v5, v109
	s_waitcnt lgkmcnt(0)
	v_sub_f32_e32 v3, v2, v3
	v_mul_f32_e32 v3, 0x3fb8aa3b, v3
	v_exp_f32_e32 v3, v3
	s_waitcnt vmcnt(2)
	v_mov_b32_e32 v6, v108
	s_waitcnt vmcnt(1)
	v_mov_b32_e32 v7, v154
	v_add_u32_e32 v6, v108, v111
	v_add_u32_e32 v5, v109, v111
	v_add_u32_e32 v4, v110, v111
	s_mov_b64 s[28:29], 0x1000
	v_lshl_add_u64 v[238:239], v[0:1], 0, s[28:29]
	v_lshl_add_u64 v[234:235], v[238:239], 0, s[28:29]
	v_lshl_add_u64 v[236:237], v[234:235], 0, s[28:29]
	ds_read_b32 v222, v6
	ds_read_b32 v226, v5
	ds_read_b32 v230, v4
	ds_read_b32 v223, v6 offset:16
	ds_read_b32 v227, v5 offset:16
	ds_read_b32 v231, v4 offset:1040
	ds_read_b32 v224, v6 offset:32
	ds_read_b32 v228, v5 offset:32
	ds_read_b32 v232, v4 offset:2080
	ds_read_b32 v225, v6 offset:48
	ds_read_b32 v229, v5 offset:48
	ds_read_b32 v233, v4 offset:3120
	s_waitcnt lgkmcnt(0)
	v_mul_f32_e32 v226, 0x3fb8aa3b, v226
	v_mul_f32_e32 v227, 0x3fb8aa3b, v227
	v_mul_f32_e32 v228, 0x3fb8aa3b, v228
	v_mul_f32_e32 v229, 0x3fb8aa3b, v229
	v_exp_f32_e32 v226, v226
	v_exp_f32_e32 v227, v227
	v_exp_f32_e32 v228, v228
	v_exp_f32_e32 v229, v229
	v_mul_f32_e32 v222, v3, v222
	v_mul_f32_e32 v223, v3, v223
	v_mul_f32_e32 v224, v3, v224
	v_mul_f32_e32 v225, v3, v225
	v_cvt_pk_bf16_f32 v222, v222, s0
	v_cvt_pk_bf16_f32 v223, v223, s0
	v_cvt_pk_bf16_f32 v224, v224, s0
	v_cvt_pk_bf16_f32 v225, v225, s0
	v_mul_f32_e32 v230, v230, v226
	v_mul_f32_e32 v231, v231, v227
	v_mul_f32_e32 v232, v232, v228
	v_mul_f32_e32 v233, v233, v229
	v_cvt_pk_bf16_f32 v230, v230, s0
	v_cvt_pk_bf16_f32 v231, v231, s0
	v_cvt_pk_bf16_f32 v232, v232, s0
	v_cvt_pk_bf16_f32 v233, v233, s0
	global_store_short v[0:1], v222, off
	global_store_short v[234:235], v230, off
	global_store_short v[0:1], v223, off offset:512
	global_store_short v[234:235], v231, off offset:512
	global_store_short v[0:1], v224, off offset:1024
	global_store_short v[234:235], v232, off offset:1024
	global_store_short v[0:1], v225, off offset:1536
	global_store_short v[234:235], v233, off offset:1536
	ds_read_b32 v222, v6 offset:64
	ds_read_b32 v226, v5 offset:64
	ds_read_b32 v230, v4 offset:4160
	ds_read_b32 v223, v6 offset:80
	ds_read_b32 v227, v5 offset:80
	ds_read_b32 v231, v4 offset:5200
	ds_read_b32 v224, v6 offset:96
	ds_read_b32 v228, v5 offset:96
	ds_read_b32 v232, v4 offset:6240
	ds_read_b32 v225, v6 offset:112
	ds_read_b32 v229, v5 offset:112
	ds_read_b32 v233, v4 offset:7280
	s_waitcnt lgkmcnt(0)
	v_mul_f32_e32 v226, 0x3fb8aa3b, v226
	v_mul_f32_e32 v227, 0x3fb8aa3b, v227
	v_mul_f32_e32 v228, 0x3fb8aa3b, v228
	v_mul_f32_e32 v229, 0x3fb8aa3b, v229
	v_exp_f32_e32 v226, v226
	v_exp_f32_e32 v227, v227
	v_exp_f32_e32 v228, v228
	v_exp_f32_e32 v229, v229
	v_mul_f32_e32 v222, v3, v222
	v_mul_f32_e32 v223, v3, v223
	v_mul_f32_e32 v224, v3, v224
	v_mul_f32_e32 v225, v3, v225
	v_cvt_pk_bf16_f32 v222, v222, s0
	v_cvt_pk_bf16_f32 v223, v223, s0
	v_cvt_pk_bf16_f32 v224, v224, s0
	v_cvt_pk_bf16_f32 v225, v225, s0
	v_mul_f32_e32 v230, v230, v226
	v_mul_f32_e32 v231, v231, v227
	v_mul_f32_e32 v232, v232, v228
	v_mul_f32_e32 v233, v233, v229
	v_cvt_pk_bf16_f32 v230, v230, s0
	v_cvt_pk_bf16_f32 v231, v231, s0
	v_cvt_pk_bf16_f32 v232, v232, s0
	v_cvt_pk_bf16_f32 v233, v233, s0
	global_store_short v[0:1], v222, off offset:2048
	global_store_short v[234:235], v230, off offset:2048
	global_store_short v[0:1], v223, off offset:2560
	global_store_short v[234:235], v231, off offset:2560
	global_store_short v[0:1], v224, off offset:3072
	global_store_short v[234:235], v232, off offset:3072
	global_store_short v[0:1], v225, off offset:3584
	global_store_short v[234:235], v233, off offset:3584
	ds_read_b32 v222, v6 offset:128
	ds_read_b32 v226, v5 offset:128
	ds_read_b32 v230, v4 offset:8320
	ds_read_b32 v223, v6 offset:144
	ds_read_b32 v227, v5 offset:144
	ds_read_b32 v231, v4 offset:9360
	ds_read_b32 v224, v6 offset:160
	ds_read_b32 v228, v5 offset:160
	ds_read_b32 v232, v4 offset:10400
	ds_read_b32 v225, v6 offset:176
	ds_read_b32 v229, v5 offset:176
	ds_read_b32 v233, v4 offset:11440
	s_waitcnt lgkmcnt(0)
	v_mul_f32_e32 v226, 0x3fb8aa3b, v226
	v_mul_f32_e32 v227, 0x3fb8aa3b, v227
	v_mul_f32_e32 v228, 0x3fb8aa3b, v228
	v_mul_f32_e32 v229, 0x3fb8aa3b, v229
	v_exp_f32_e32 v226, v226
	v_exp_f32_e32 v227, v227
	v_exp_f32_e32 v228, v228
	v_exp_f32_e32 v229, v229
	v_mul_f32_e32 v222, v3, v222
	v_mul_f32_e32 v223, v3, v223
	v_mul_f32_e32 v224, v3, v224
	v_mul_f32_e32 v225, v3, v225
	v_cvt_pk_bf16_f32 v222, v222, s0
	v_cvt_pk_bf16_f32 v223, v223, s0
	v_cvt_pk_bf16_f32 v224, v224, s0
	v_cvt_pk_bf16_f32 v225, v225, s0
	v_mul_f32_e32 v230, v230, v226
	v_mul_f32_e32 v231, v231, v227
	v_mul_f32_e32 v232, v232, v228
	v_mul_f32_e32 v233, v233, v229
	v_cvt_pk_bf16_f32 v230, v230, s0
	v_cvt_pk_bf16_f32 v231, v231, s0
	v_cvt_pk_bf16_f32 v232, v232, s0
	v_cvt_pk_bf16_f32 v233, v233, s0
	global_store_short v[238:239], v222, off
	global_store_short v[236:237], v230, off
	global_store_short v[238:239], v223, off offset:512
	global_store_short v[236:237], v231, off offset:512
	global_store_short v[238:239], v224, off offset:1024
	global_store_short v[236:237], v232, off offset:1024
	global_store_short v[238:239], v225, off offset:1536
	global_store_short v[236:237], v233, off offset:1536
	ds_read_b32 v222, v6 offset:192
	ds_read_b32 v226, v5 offset:192
	ds_read_b32 v230, v4 offset:12480
	ds_read_b32 v223, v6 offset:208
	ds_read_b32 v227, v5 offset:208
	ds_read_b32 v231, v4 offset:13520
	ds_read_b32 v224, v6 offset:224
	ds_read_b32 v228, v5 offset:224
	ds_read_b32 v232, v4 offset:14560
	ds_read_b32 v225, v6 offset:240
	ds_read_b32 v229, v5 offset:240
	ds_read_b32 v233, v4 offset:15600
	s_waitcnt lgkmcnt(0)
; #define LAS __attribute__((address_space(3)))
; __device__ __forceinline__ unsigned f2bf(float f) { const f32x2_ v = {f, 0.f}; const bf16x2_ b = __builtin_convertvector(v, bf16x2_); return __builtin_bit_cast(unsigned, b) & 0xffffu; }
; #define LBAR() asm volatile("s_waitcnt lgkmcnt(0)\n\ts_barrier" ::: "memory")
; __device__ __forceinline__ void g1_phase(const PP P, int l, LAS unsigned char* lds) {
;     ...
;         if (act) {
;             const float glast = Gs[63];
;             for (int e = gt; e < 4096; e += 256) { const int hi = e >> 6, lo = e & 63;
;                 KdT[e] = (bf16)f2bf(ks[lo * 65 + hi] * __expf(glast - Gs[lo]));
;                 QG[e] = (bf16)f2bf(qs[hi * 65 + lo] * __expf(Gs[hi])); }
;             if (gt == 0) *(float*)(ub + 49152) = __expf(glast);
;         }
;         LBAR();
;     ...
;         }
;     ...
;         if (act) {
;             for (int e = gt; e < 8192; e += 256) { const int i = e >> 7, c = e & 127; LAS float* p = ((c < 64) ? ks : vs) + i * 65 + (c & 63);
;                 *p = *p * bs[i] * ((c < 64) ? __expf(Gs[i]) : 1.0f); }
;         }
	v_mul_f32_e32 v226, 0x3fb8aa3b, v226
	v_mul_f32_e32 v227, 0x3fb8aa3b, v227
	v_mul_f32_e32 v228, 0x3fb8aa3b, v228
	v_mul_f32_e32 v229, 0x3fb8aa3b, v229
	v_exp_f32_e32 v226, v226
	v_exp_f32_e32 v227, v227
	v_exp_f32_e32 v228, v228
	v_exp_f32_e32 v229, v229
	v_mul_f32_e32 v222, v3, v222
	v_mul_f32_e32 v223, v3, v223
	v_mul_f32_e32 v224, v3, v224
	v_mul_f32_e32 v225, v3, v225
	v_cvt_pk_bf16_f32 v222, v222, s0
	v_cvt_pk_bf16_f32 v223, v223, s0
	v_cvt_pk_bf16_f32 v224, v224, s0
	v_cvt_pk_bf16_f32 v225, v225, s0
	v_mul_f32_e32 v230, v230, v226
	v_mul_f32_e32 v231, v231, v227
	v_mul_f32_e32 v232, v232, v228
	v_mul_f32_e32 v233, v233, v229
	v_cvt_pk_bf16_f32 v230, v230, s0
	v_cvt_pk_bf16_f32 v231, v231, s0
	v_cvt_pk_bf16_f32 v232, v232, s0
	v_cvt_pk_bf16_f32 v233, v233, s0
	global_store_short v[238:239], v222, off offset:2048
	global_store_short v[236:237], v230, off offset:2048
	global_store_short v[238:239], v223, off offset:2560
	global_store_short v[236:237], v231, off offset:2560
	global_store_short v[238:239], v224, off offset:3072
	global_store_short v[236:237], v232, off offset:3072
	global_store_short v[238:239], v225, off offset:3584
	global_store_short v[236:237], v233, off offset:3584
	s_or_b64 exec, exec, s[78:79]
	s_and_b64 exec, exec, s[12:13]
	s_cbranch_execz .LBB0_599
	v_mul_f32_e32 v0, 0x3fb8aa3b, v2
	v_exp_f32_e32 v2, v0
	v_add_co_u32_e32 v0, vcc, 0xc000, v70
	s_nop 1
	v_addc_co_u32_e32 v1, vcc, 0, v71, vcc
	global_store_dword v[0:1], v2, off
.LBB0_599:
	s_or_b64 exec, exec, s[26:27]
	s_waitcnt lgkmcnt(0)
	s_barrier
	s_mov_b64 s[26:27], 0
	s_and_saveexec_b64 s[78:79], s[76:77]
	s_cbranch_execz .LBB0_605
	v_and_b32_e32 v3, 64, v28
	v_cmp_eq_u32_e32 vcc, 0, v3
	v_mul_u32_u24_e32 v4, 0x104, v112
	s_nop 1
	v_cndmask_b32_e32 v3, v83, v82, vcc
	v_add3_u32 v3, v3, v4, v26
	ds_read_b32 v222, v3
	ds_read_b32 v226, v113 offset:256
	ds_read_b32 v230, v113
	ds_read_b32 v223, v3 offset:520
	ds_read_b32 v227, v113 offset:264
	ds_read_b32 v231, v113 offset:8
	ds_read_b32 v224, v3 offset:1040
	ds_read_b32 v228, v113 offset:272
	ds_read_b32 v232, v113 offset:16
	ds_read_b32 v225, v3 offset:1560
	ds_read_b32 v229, v113 offset:280
	ds_read_b32 v233, v113 offset:24
	s_waitcnt lgkmcnt(0)
	v_mul_f32_e32 v230, 0x3fb8aa3b, v230
	v_mul_f32_e32 v231, 0x3fb8aa3b, v231
	v_mul_f32_e32 v232, 0x3fb8aa3b, v232
	v_mul_f32_e32 v233, 0x3fb8aa3b, v233
	v_exp_f32_e32 v230, v230
	v_exp_f32_e32 v231, v231
	v_exp_f32_e32 v232, v232
	v_exp_f32_e32 v233, v233
	v_mul_f32_e32 v222, v222, v226
	v_mul_f32_e32 v223, v223, v227
	v_mul_f32_e32 v224, v224, v228
	v_mul_f32_e32 v225, v225, v229
	v_cndmask_b32_e32 v230, 1.0, v230, vcc
	v_cndmask_b32_e32 v231, 1.0, v231, vcc
	v_cndmask_b32_e32 v232, 1.0, v232, vcc
	v_cndmask_b32_e32 v233, 1.0, v233, vcc
	v_mul_f32_e32 v222, v222, v230
	v_mul_f32_e32 v223, v223, v231
	v_mul_f32_e32 v224, v224, v232
	v_mul_f32_e32 v225, v225, v233
	ds_write_b32 v3, v222
	ds_write_b32 v3, v223 offset:520
	ds_write_b32 v3, v224 offset:1040
	ds_write_b32 v3, v225 offset:1560
	ds_read_b32 v222, v3 offset:2080
	ds_read_b32 v226, v113 offset:288
	ds_read_b32 v230, v113 offset:32
	ds_read_b32 v223, v3 offset:2600
	ds_read_b32 v227, v113 offset:296
	ds_read_b32 v231, v113 offset:40
	ds_read_b32 v224, v3 offset:3120
	ds_read_b32 v228, v113 offset:304
	ds_read_b32 v232, v113 offset:48
	ds_read_b32 v225, v3 offset:3640
	ds_read_b32 v229, v113 offset:312
	ds_read_b32 v233, v113 offset:56
	s_waitcnt lgkmcnt(0)
	v_mul_f32_e32 v230, 0x3fb8aa3b, v230
	v_mul_f32_e32 v231, 0x3fb8aa3b, v231
	v_mul_f32_e32 v232, 0x3fb8aa3b, v232
	v_mul_f32_e32 v233, 0x3fb8aa3b, v233
	v_exp_f32_e32 v230, v230
	v_exp_f32_e32 v231, v231
	v_exp_f32_e32 v232, v232
	v_exp_f32_e32 v233, v233
	v_mul_f32_e32 v222, v222, v226
	v_mul_f32_e32 v223, v223, v227
	v_mul_f32_e32 v224, v224, v228
	v_mul_f32_e32 v225, v225, v229
	v_cndmask_b32_e32 v230, 1.0, v230, vcc
	v_cndmask_b32_e32 v231, 1.0, v231, vcc
	v_cndmask_b32_e32 v232, 1.0, v232, vcc
	v_cndmask_b32_e32 v233, 1.0, v233, vcc
	v_mul_f32_e32 v222, v222, v230
	v_mul_f32_e32 v223, v223, v231
	v_mul_f32_e32 v224, v224, v232
	v_mul_f32_e32 v225, v225, v233
	ds_write_b32 v3, v222 offset:2080
	ds_write_b32 v3, v223 offset:2600
	ds_write_b32 v3, v224 offset:3120
	ds_write_b32 v3, v225 offset:3640
	ds_read_b32 v222, v3 offset:4160
	ds_read_b32 v226, v113 offset:320
	ds_read_b32 v230, v113 offset:64
	ds_read_b32 v223, v3 offset:4680
	ds_read_b32 v227, v113 offset:328
	ds_read_b32 v231, v113 offset:72
	ds_read_b32 v224, v3 offset:5200
	ds_read_b32 v228, v113 offset:336
	ds_read_b32 v232, v113 offset:80
	ds_read_b32 v225, v3 offset:5720
	ds_read_b32 v229, v113 offset:344
	ds_read_b32 v233, v113 offset:88
	s_waitcnt lgkmcnt(0)
	v_mul_f32_e32 v230, 0x3fb8aa3b, v230
	v_mul_f32_e32 v231, 0x3fb8aa3b, v231
	v_mul_f32_e32 v232, 0x3fb8aa3b, v232
	v_mul_f32_e32 v233, 0x3fb8aa3b, v233
	v_exp_f32_e32 v230, v230
	v_exp_f32_e32 v231, v231
	v_exp_f32_e32 v232, v232
	v_exp_f32_e32 v233, v233
	v_mul_f32_e32 v222, v222, v226
	v_mul_f32_e32 v223, v223, v227
	v_mul_f32_e32 v224, v224, v228
	v_mul_f32_e32 v225, v225, v229
	v_cndmask_b32_e32 v230, 1.0, v230, vcc
	v_cndmask_b32_e32 v231, 1.0, v231, vcc
	v_cndmask_b32_e32 v232, 1.0, v232, vcc
	v_cndmask_b32_e32 v233, 1.0, v233, vcc
	v_mul_f32_e32 v222, v222, v230
	v_mul_f32_e32 v223, v223, v231
	v_mul_f32_e32 v224, v224, v232
	v_mul_f32_e32 v225, v225, v233
	ds_write_b32 v3, v222 offset:4160
	ds_write_b32 v3, v223 offset:4680
	ds_write_b32 v3, v224 offset:5200
	ds_write_b32 v3, v225 offset:5720
	ds_read_b32 v222, v3 offset:6240
	ds_read_b32 v226, v113 offset:352
	ds_read_b32 v230, v113 offset:96
	ds_read_b32 v223, v3 offset:6760
	ds_read_b32 v227, v113 offset:360
	ds_read_b32 v231, v113 offset:104
	ds_read_b32 v224, v3 offset:7280
	ds_read_b32 v228, v113 offset:368
	ds_read_b32 v232, v113 offset:112
	ds_read_b32 v225, v3 offset:7800
	ds_read_b32 v229, v113 offset:376
	ds_read_b32 v233, v113 offset:120
	s_waitcnt lgkmcnt(0)
; #define LAS __attribute__((address_space(3)))
; __device__ __forceinline__ void g1_phase(const PP P, int l, LAS unsigned char* lds) {
;     ...
;         if (act) {
;             for (int e = gt; e < 8192; e += 256) { const int i = e >> 7, c = e & 127; LAS float* p = ((c < 64) ? ks : vs) + i * 65 + (c & 63);
;                 *p = *p * bs[i] * ((c < 64) ? __expf(Gs[i]) : 1.0f); }
;         }
	v_mul_f32_e32 v230, 0x3fb8aa3b, v230
	v_mul_f32_e32 v231, 0x3fb8aa3b, v231
	v_mul_f32_e32 v232, 0x3fb8aa3b, v232
	v_mul_f32_e32 v233, 0x3fb8aa3b, v233
	v_exp_f32_e32 v230, v230
	v_exp_f32_e32 v231, v231
	v_exp_f32_e32 v232, v232
	v_exp_f32_e32 v233, v233
	v_mul_f32_e32 v222, v222, v226
	v_mul_f32_e32 v223, v223, v227
	v_mul_f32_e32 v224, v224, v228
	v_mul_f32_e32 v225, v225, v229
	v_cndmask_b32_e32 v230, 1.0, v230, vcc
	v_cndmask_b32_e32 v231, 1.0, v231, vcc
	v_cndmask_b32_e32 v232, 1.0, v232, vcc
	v_cndmask_b32_e32 v233, 1.0, v233, vcc
	v_mul_f32_e32 v222, v222, v230
	v_mul_f32_e32 v223, v223, v231
	v_mul_f32_e32 v224, v224, v232
	v_mul_f32_e32 v225, v225, v233
	ds_write_b32 v3, v222 offset:6240
	ds_write_b32 v3, v223 offset:6760
	ds_write_b32 v3, v224 offset:7280
	ds_write_b32 v3, v225 offset:7800
	ds_read_b32 v222, v3 offset:8320
	ds_read_b32 v226, v113 offset:384
	ds_read_b32 v230, v113 offset:128
	ds_read_b32 v223, v3 offset:8840
	ds_read_b32 v227, v113 offset:392
	ds_read_b32 v231, v113 offset:136
	ds_read_b32 v224, v3 offset:9360
	ds_read_b32 v228, v113 offset:400
	ds_read_b32 v232, v113 offset:144
	ds_read_b32 v225, v3 offset:9880
	ds_read_b32 v229, v113 offset:408
	ds_read_b32 v233, v113 offset:152
	s_waitcnt lgkmcnt(0)
	v_mul_f32_e32 v230, 0x3fb8aa3b, v230
	v_mul_f32_e32 v231, 0x3fb8aa3b, v231
	v_mul_f32_e32 v232, 0x3fb8aa3b, v232
	v_mul_f32_e32 v233, 0x3fb8aa3b, v233
	v_exp_f32_e32 v230, v230
	v_exp_f32_e32 v231, v231
	v_exp_f32_e32 v232, v232
	v_exp_f32_e32 v233, v233
	v_mul_f32_e32 v222, v222, v226
	v_mul_f32_e32 v223, v223, v227
	v_mul_f32_e32 v224, v224, v228
	v_mul_f32_e32 v225, v225, v229
	v_cndmask_b32_e32 v230, 1.0, v230, vcc
	v_cndmask_b32_e32 v231, 1.0, v231, vcc
	v_cndmask_b32_e32 v232, 1.0, v232, vcc
	v_cndmask_b32_e32 v233, 1.0, v233, vcc
	v_mul_f32_e32 v222, v222, v230
	v_mul_f32_e32 v223, v223, v231
	v_mul_f32_e32 v224, v224, v232
	v_mul_f32_e32 v225, v225, v233
	ds_write_b32 v3, v222 offset:8320
	ds_write_b32 v3, v223 offset:8840
	ds_write_b32 v3, v224 offset:9360
	ds_write_b32 v3, v225 offset:9880
	ds_read_b32 v222, v3 offset:10400
	ds_read_b32 v226, v113 offset:416
	ds_read_b32 v230, v113 offset:160
	ds_read_b32 v223, v3 offset:10920
	ds_read_b32 v227, v113 offset:424
	ds_read_b32 v231, v113 offset:168
	ds_read_b32 v224, v3 offset:11440
	ds_read_b32 v228, v113 offset:432
	ds_read_b32 v232, v113 offset:176
	ds_read_b32 v225, v3 offset:11960
	ds_read_b32 v229, v113 offset:440
	ds_read_b32 v233, v113 offset:184
	s_waitcnt lgkmcnt(0)
	v_mul_f32_e32 v230, 0x3fb8aa3b, v230
	v_mul_f32_e32 v231, 0x3fb8aa3b, v231
	v_mul_f32_e32 v232, 0x3fb8aa3b, v232
	v_mul_f32_e32 v233, 0x3fb8aa3b, v233
	v_exp_f32_e32 v230, v230
	v_exp_f32_e32 v231, v231
	v_exp_f32_e32 v232, v232
	v_exp_f32_e32 v233, v233
	v_mul_f32_e32 v222, v222, v226
	v_mul_f32_e32 v223, v223, v227
	v_mul_f32_e32 v224, v224, v228
	v_mul_f32_e32 v225, v225, v229
	v_cndmask_b32_e32 v230, 1.0, v230, vcc
	v_cndmask_b32_e32 v231, 1.0, v231, vcc
	v_cndmask_b32_e32 v232, 1.0, v232, vcc
	v_cndmask_b32_e32 v233, 1.0, v233, vcc
	v_mul_f32_e32 v222, v222, v230
	v_mul_f32_e32 v223, v223, v231
	v_mul_f32_e32 v224, v224, v232
	v_mul_f32_e32 v225, v225, v233
	ds_write_b32 v3, v222 offset:10400
	ds_write_b32 v3, v223 offset:10920
	ds_write_b32 v3, v224 offset:11440
	ds_write_b32 v3, v225 offset:11960
	ds_read_b32 v222, v3 offset:12480
	ds_read_b32 v226, v113 offset:448
	ds_read_b32 v230, v113 offset:192
	ds_read_b32 v223, v3 offset:13000
	ds_read_b32 v227, v113 offset:456
	ds_read_b32 v231, v113 offset:200
	ds_read_b32 v224, v3 offset:13520
	ds_read_b32 v228, v113 offset:464
	ds_read_b32 v232, v113 offset:208
	ds_read_b32 v225, v3 offset:14040
	ds_read_b32 v229, v113 offset:472
	ds_read_b32 v233, v113 offset:216
	s_waitcnt lgkmcnt(0)
	v_mul_f32_e32 v230, 0x3fb8aa3b, v230
	v_mul_f32_e32 v231, 0x3fb8aa3b, v231
	v_mul_f32_e32 v232, 0x3fb8aa3b, v232
	v_mul_f32_e32 v233, 0x3fb8aa3b, v233
	v_exp_f32_e32 v230, v230
	v_exp_f32_e32 v231, v231
	v_exp_f32_e32 v232, v232
	v_exp_f32_e32 v233, v233
	v_mul_f32_e32 v222, v222, v226
	v_mul_f32_e32 v223, v223, v227
	v_mul_f32_e32 v224, v224, v228
	v_mul_f32_e32 v225, v225, v229
	v_cndmask_b32_e32 v230, 1.0, v230, vcc
	v_cndmask_b32_e32 v231, 1.0, v231, vcc
	v_cndmask_b32_e32 v232, 1.0, v232, vcc
	v_cndmask_b32_e32 v233, 1.0, v233, vcc
	v_mul_f32_e32 v222, v222, v230
	v_mul_f32_e32 v223, v223, v231
	v_mul_f32_e32 v224, v224, v232
	v_mul_f32_e32 v225, v225, v233
	ds_write_b32 v3, v222 offset:12480
	ds_write_b32 v3, v223 offset:13000
	ds_write_b32 v3, v224 offset:13520
	ds_write_b32 v3, v225 offset:14040
	ds_read_b32 v222, v3 offset:14560
	ds_read_b32 v226, v113 offset:480
	ds_read_b32 v230, v113 offset:224
	ds_read_b32 v223, v3 offset:15080
	ds_read_b32 v227, v113 offset:488
	ds_read_b32 v231, v113 offset:232
	ds_read_b32 v224, v3 offset:15600
	ds_read_b32 v228, v113 offset:496
	ds_read_b32 v232, v113 offset:240
	ds_read_b32 v225, v3 offset:16120
	ds_read_b32 v229, v113 offset:504
	ds_read_b32 v233, v113 offset:248
	s_waitcnt lgkmcnt(0)
	v_mul_f32_e32 v230, 0x3fb8aa3b, v230
	v_mul_f32_e32 v231, 0x3fb8aa3b, v231
	v_mul_f32_e32 v232, 0x3fb8aa3b, v232
	v_mul_f32_e32 v233, 0x3fb8aa3b, v233
	v_exp_f32_e32 v230, v230
	v_exp_f32_e32 v231, v231
	v_exp_f32_e32 v232, v232
	v_exp_f32_e32 v233, v233
	v_mul_f32_e32 v222, v222, v226
	v_mul_f32_e32 v223, v223, v227
	v_mul_f32_e32 v224, v224, v228
	v_mul_f32_e32 v225, v225, v229
	v_cndmask_b32_e32 v230, 1.0, v230, vcc
	v_cndmask_b32_e32 v231, 1.0, v231, vcc
	v_cndmask_b32_e32 v232, 1.0, v232, vcc
	v_cndmask_b32_e32 v233, 1.0, v233, vcc
	v_mul_f32_e32 v222, v222, v230
	v_mul_f32_e32 v223, v223, v231
	v_mul_f32_e32 v224, v224, v232
	v_mul_f32_e32 v225, v225, v233
	ds_write_b32 v3, v222 offset:14560
	ds_write_b32 v3, v223 offset:15080
	ds_write_b32 v3, v224 offset:15600
	ds_write_b32 v3, v225 offset:16120
